# instruction selection in ln2 consume blocks: v_cvt_pk_f32_fp8 (2 per dword) instead of four single fp8->f32 converts
# speedup vs baseline: 1.0066x; 1.0066x over previous
.Lg_cons4:
	s_waitcnt vmcnt(12)
	v_cvt_pk_f32_fp8_e32 v[78:79], v96
	v_cvt_pk_f32_fp8_sdwa v[80:81], v96 src0_sel:WORD_1
	v_cvt_pk_f32_fp8_e32 v[82:83], v97
	v_cvt_pk_f32_fp8_sdwa v[84:85], v97 src0_sel:WORD_1
	v_cvt_pk_f32_fp8_e32 v[86:87], v98
	v_cvt_pk_f32_fp8_sdwa v[88:89], v98 src0_sel:WORD_1
	v_cvt_pk_f32_fp8_e32 v[90:91], v99
	v_cvt_pk_f32_fp8_sdwa v[92:93], v99 src0_sel:WORD_1
	v_pk_fma_f32 v[64:65], v[78:79], s[6:7], v[64:65] op_sel_hi:[1,0,1]
	v_pk_fma_f32 v[62:63], v[80:81], s[6:7], v[62:63] op_sel_hi:[1,0,1]
	v_pk_fma_f32 v[60:61], v[82:83], s[6:7], v[60:61] op_sel_hi:[1,0,1]
	v_pk_fma_f32 v[58:59], v[84:85], s[6:7], v[58:59] op_sel_hi:[1,0,1]
	v_pk_fma_f32 v[56:57], v[86:87], s[6:7], v[56:57] op_sel_hi:[1,0,1]
	v_pk_fma_f32 v[54:55], v[88:89], s[6:7], v[54:55] op_sel_hi:[1,0,1]
	v_pk_fma_f32 v[50:51], v[90:91], s[6:7], v[50:51] op_sel_hi:[1,0,1]
	v_pk_fma_f32 v[52:53], v[92:93], s[6:7], v[52:53] op_sel_hi:[1,0,1]
	s_waitcnt vmcnt(8)
	v_cvt_pk_f32_fp8_e32 v[78:79], v100
	v_cvt_pk_f32_fp8_sdwa v[80:81], v100 src0_sel:WORD_1
	v_cvt_pk_f32_fp8_e32 v[82:83], v101
	v_cvt_pk_f32_fp8_sdwa v[84:85], v101 src0_sel:WORD_1
	v_cvt_pk_f32_fp8_e32 v[86:87], v102
	v_cvt_pk_f32_fp8_sdwa v[88:89], v102 src0_sel:WORD_1
	v_cvt_pk_f32_fp8_e32 v[90:91], v103
	v_cvt_pk_f32_fp8_sdwa v[92:93], v103 src0_sel:WORD_1
	v_pk_fma_f32 v[64:65], v[78:79], s[6:7], v[64:65] op_sel_hi:[1,0,1]
	v_pk_fma_f32 v[62:63], v[80:81], s[6:7], v[62:63] op_sel_hi:[1,0,1]
	v_pk_fma_f32 v[60:61], v[82:83], s[6:7], v[60:61] op_sel_hi:[1,0,1]
	v_pk_fma_f32 v[58:59], v[84:85], s[6:7], v[58:59] op_sel_hi:[1,0,1]
	v_pk_fma_f32 v[56:57], v[86:87], s[6:7], v[56:57] op_sel_hi:[1,0,1]
	v_pk_fma_f32 v[54:55], v[88:89], s[6:7], v[54:55] op_sel_hi:[1,0,1]
	v_pk_fma_f32 v[50:51], v[90:91], s[6:7], v[50:51] op_sel_hi:[1,0,1]
	v_pk_fma_f32 v[52:53], v[92:93], s[6:7], v[52:53] op_sel_hi:[1,0,1]
	s_waitcnt vmcnt(4)
	v_cvt_pk_f32_fp8_e32 v[78:79], v104
	v_cvt_pk_f32_fp8_sdwa v[80:81], v104 src0_sel:WORD_1
	v_cvt_pk_f32_fp8_e32 v[82:83], v105
	v_cvt_pk_f32_fp8_sdwa v[84:85], v105 src0_sel:WORD_1
	v_cvt_pk_f32_fp8_e32 v[86:87], v106
	v_cvt_pk_f32_fp8_sdwa v[88:89], v106 src0_sel:WORD_1
	v_cvt_pk_f32_fp8_e32 v[90:91], v107
	v_cvt_pk_f32_fp8_sdwa v[92:93], v107 src0_sel:WORD_1
	v_pk_fma_f32 v[64:65], v[78:79], s[6:7], v[64:65] op_sel_hi:[1,0,1]
	v_pk_fma_f32 v[62:63], v[80:81], s[6:7], v[62:63] op_sel_hi:[1,0,1]
	v_pk_fma_f32 v[60:61], v[82:83], s[6:7], v[60:61] op_sel_hi:[1,0,1]
	v_pk_fma_f32 v[58:59], v[84:85], s[6:7], v[58:59] op_sel_hi:[1,0,1]
	v_pk_fma_f32 v[56:57], v[86:87], s[6:7], v[56:57] op_sel_hi:[1,0,1]
	v_pk_fma_f32 v[54:55], v[88:89], s[6:7], v[54:55] op_sel_hi:[1,0,1]
	v_pk_fma_f32 v[50:51], v[90:91], s[6:7], v[50:51] op_sel_hi:[1,0,1]
	v_pk_fma_f32 v[52:53], v[92:93], s[6:7], v[52:53] op_sel_hi:[1,0,1]
	s_waitcnt vmcnt(0)
	v_cvt_pk_f32_fp8_e32 v[78:79], v108
	v_cvt_pk_f32_fp8_sdwa v[80:81], v108 src0_sel:WORD_1
	v_cvt_pk_f32_fp8_e32 v[82:83], v109
	v_cvt_pk_f32_fp8_sdwa v[84:85], v109 src0_sel:WORD_1
	v_cvt_pk_f32_fp8_e32 v[86:87], v110
	v_cvt_pk_f32_fp8_sdwa v[88:89], v110 src0_sel:WORD_1
	v_cvt_pk_f32_fp8_e32 v[90:91], v111
	v_cvt_pk_f32_fp8_sdwa v[92:93], v111 src0_sel:WORD_1
	v_pk_fma_f32 v[64:65], v[78:79], s[6:7], v[64:65] op_sel_hi:[1,0,1]
	v_pk_fma_f32 v[62:63], v[80:81], s[6:7], v[62:63] op_sel_hi:[1,0,1]
	v_pk_fma_f32 v[60:61], v[82:83], s[6:7], v[60:61] op_sel_hi:[1,0,1]
	v_pk_fma_f32 v[58:59], v[84:85], s[6:7], v[58:59] op_sel_hi:[1,0,1]
	v_pk_fma_f32 v[56:57], v[86:87], s[6:7], v[56:57] op_sel_hi:[1,0,1]
	v_pk_fma_f32 v[54:55], v[88:89], s[6:7], v[54:55] op_sel_hi:[1,0,1]
	v_pk_fma_f32 v[50:51], v[90:91], s[6:7], v[50:51] op_sel_hi:[1,0,1]
	v_pk_fma_f32 v[52:53], v[92:93], s[6:7], v[52:53] op_sel_hi:[1,0,1]
	s_branch .Lg_scan0
.Lg_cons3:
	s_waitcnt vmcnt(8)
	v_cvt_pk_f32_fp8_e32 v[78:79], v96
	v_cvt_pk_f32_fp8_sdwa v[80:81], v96 src0_sel:WORD_1
	v_cvt_pk_f32_fp8_e32 v[82:83], v97
	v_cvt_pk_f32_fp8_sdwa v[84:85], v97 src0_sel:WORD_1
	v_cvt_pk_f32_fp8_e32 v[86:87], v98
	v_cvt_pk_f32_fp8_sdwa v[88:89], v98 src0_sel:WORD_1
	v_cvt_pk_f32_fp8_e32 v[90:91], v99
	v_cvt_pk_f32_fp8_sdwa v[92:93], v99 src0_sel:WORD_1
	v_pk_fma_f32 v[64:65], v[78:79], s[6:7], v[64:65] op_sel_hi:[1,0,1]
	v_pk_fma_f32 v[62:63], v[80:81], s[6:7], v[62:63] op_sel_hi:[1,0,1]
	v_pk_fma_f32 v[60:61], v[82:83], s[6:7], v[60:61] op_sel_hi:[1,0,1]
	v_pk_fma_f32 v[58:59], v[84:85], s[6:7], v[58:59] op_sel_hi:[1,0,1]
	v_pk_fma_f32 v[56:57], v[86:87], s[6:7], v[56:57] op_sel_hi:[1,0,1]
	v_pk_fma_f32 v[54:55], v[88:89], s[6:7], v[54:55] op_sel_hi:[1,0,1]
	v_pk_fma_f32 v[50:51], v[90:91], s[6:7], v[50:51] op_sel_hi:[1,0,1]
	v_pk_fma_f32 v[52:53], v[92:93], s[6:7], v[52:53] op_sel_hi:[1,0,1]
	s_waitcnt vmcnt(4)
	v_cvt_pk_f32_fp8_e32 v[78:79], v100
	v_cvt_pk_f32_fp8_sdwa v[80:81], v100 src0_sel:WORD_1
	v_cvt_pk_f32_fp8_e32 v[82:83], v101
	v_cvt_pk_f32_fp8_sdwa v[84:85], v101 src0_sel:WORD_1
	v_cvt_pk_f32_fp8_e32 v[86:87], v102
	v_cvt_pk_f32_fp8_sdwa v[88:89], v102 src0_sel:WORD_1
	v_cvt_pk_f32_fp8_e32 v[90:91], v103
	v_cvt_pk_f32_fp8_sdwa v[92:93], v103 src0_sel:WORD_1
	v_pk_fma_f32 v[64:65], v[78:79], s[6:7], v[64:65] op_sel_hi:[1,0,1]
	v_pk_fma_f32 v[62:63], v[80:81], s[6:7], v[62:63] op_sel_hi:[1,0,1]
	v_pk_fma_f32 v[60:61], v[82:83], s[6:7], v[60:61] op_sel_hi:[1,0,1]
	v_pk_fma_f32 v[58:59], v[84:85], s[6:7], v[58:59] op_sel_hi:[1,0,1]
	v_pk_fma_f32 v[56:57], v[86:87], s[6:7], v[56:57] op_sel_hi:[1,0,1]
	v_pk_fma_f32 v[54:55], v[88:89], s[6:7], v[54:55] op_sel_hi:[1,0,1]
	v_pk_fma_f32 v[50:51], v[90:91], s[6:7], v[50:51] op_sel_hi:[1,0,1]
	v_pk_fma_f32 v[52:53], v[92:93], s[6:7], v[52:53] op_sel_hi:[1,0,1]
	s_waitcnt vmcnt(0)
	v_cvt_pk_f32_fp8_e32 v[78:79], v104
	v_cvt_pk_f32_fp8_sdwa v[80:81], v104 src0_sel:WORD_1
	v_cvt_pk_f32_fp8_e32 v[82:83], v105
	v_cvt_pk_f32_fp8_sdwa v[84:85], v105 src0_sel:WORD_1
	v_cvt_pk_f32_fp8_e32 v[86:87], v106
	v_cvt_pk_f32_fp8_sdwa v[88:89], v106 src0_sel:WORD_1
	v_cvt_pk_f32_fp8_e32 v[90:91], v107
	v_cvt_pk_f32_fp8_sdwa v[92:93], v107 src0_sel:WORD_1
	v_pk_fma_f32 v[64:65], v[78:79], s[6:7], v[64:65] op_sel_hi:[1,0,1]
	v_pk_fma_f32 v[62:63], v[80:81], s[6:7], v[62:63] op_sel_hi:[1,0,1]
	v_pk_fma_f32 v[60:61], v[82:83], s[6:7], v[60:61] op_sel_hi:[1,0,1]
	v_pk_fma_f32 v[58:59], v[84:85], s[6:7], v[58:59] op_sel_hi:[1,0,1]
	v_pk_fma_f32 v[56:57], v[86:87], s[6:7], v[56:57] op_sel_hi:[1,0,1]
	v_pk_fma_f32 v[54:55], v[88:89], s[6:7], v[54:55] op_sel_hi:[1,0,1]
	v_pk_fma_f32 v[50:51], v[90:91], s[6:7], v[50:51] op_sel_hi:[1,0,1]
	v_pk_fma_f32 v[52:53], v[92:93], s[6:7], v[52:53] op_sel_hi:[1,0,1]
	s_branch .LBB0_1393
.Lg_cons2:
	s_waitcnt vmcnt(4)
	v_cvt_pk_f32_fp8_e32 v[78:79], v96
	v_cvt_pk_f32_fp8_sdwa v[80:81], v96 src0_sel:WORD_1
	v_cvt_pk_f32_fp8_e32 v[82:83], v97
	v_cvt_pk_f32_fp8_sdwa v[84:85], v97 src0_sel:WORD_1
	v_cvt_pk_f32_fp8_e32 v[86:87], v98
	v_cvt_pk_f32_fp8_sdwa v[88:89], v98 src0_sel:WORD_1
	v_cvt_pk_f32_fp8_e32 v[90:91], v99
	v_cvt_pk_f32_fp8_sdwa v[92:93], v99 src0_sel:WORD_1
	v_pk_fma_f32 v[64:65], v[78:79], s[6:7], v[64:65] op_sel_hi:[1,0,1]
	v_pk_fma_f32 v[62:63], v[80:81], s[6:7], v[62:63] op_sel_hi:[1,0,1]
	v_pk_fma_f32 v[60:61], v[82:83], s[6:7], v[60:61] op_sel_hi:[1,0,1]
	v_pk_fma_f32 v[58:59], v[84:85], s[6:7], v[58:59] op_sel_hi:[1,0,1]
	v_pk_fma_f32 v[56:57], v[86:87], s[6:7], v[56:57] op_sel_hi:[1,0,1]
	v_pk_fma_f32 v[54:55], v[88:89], s[6:7], v[54:55] op_sel_hi:[1,0,1]
	v_pk_fma_f32 v[50:51], v[90:91], s[6:7], v[50:51] op_sel_hi:[1,0,1]
	v_pk_fma_f32 v[52:53], v[92:93], s[6:7], v[52:53] op_sel_hi:[1,0,1]
	s_waitcnt vmcnt(0)
	v_cvt_pk_f32_fp8_e32 v[78:79], v100
	v_cvt_pk_f32_fp8_sdwa v[80:81], v100 src0_sel:WORD_1
	v_cvt_pk_f32_fp8_e32 v[82:83], v101
	v_cvt_pk_f32_fp8_sdwa v[84:85], v101 src0_sel:WORD_1
	v_cvt_pk_f32_fp8_e32 v[86:87], v102
	v_cvt_pk_f32_fp8_sdwa v[88:89], v102 src0_sel:WORD_1
	v_cvt_pk_f32_fp8_e32 v[90:91], v103
	v_cvt_pk_f32_fp8_sdwa v[92:93], v103 src0_sel:WORD_1
	v_pk_fma_f32 v[64:65], v[78:79], s[6:7], v[64:65] op_sel_hi:[1,0,1]
	v_pk_fma_f32 v[62:63], v[80:81], s[6:7], v[62:63] op_sel_hi:[1,0,1]
	v_pk_fma_f32 v[60:61], v[82:83], s[6:7], v[60:61] op_sel_hi:[1,0,1]
	v_pk_fma_f32 v[58:59], v[84:85], s[6:7], v[58:59] op_sel_hi:[1,0,1]
	v_pk_fma_f32 v[56:57], v[86:87], s[6:7], v[56:57] op_sel_hi:[1,0,1]
	v_pk_fma_f32 v[54:55], v[88:89], s[6:7], v[54:55] op_sel_hi:[1,0,1]
	v_pk_fma_f32 v[50:51], v[90:91], s[6:7], v[50:51] op_sel_hi:[1,0,1]
	v_pk_fma_f32 v[52:53], v[92:93], s[6:7], v[52:53] op_sel_hi:[1,0,1]
	s_branch .LBB0_1393
.Lg_cons1:
	s_waitcnt vmcnt(0)
	v_cvt_pk_f32_fp8_e32 v[78:79], v96
	v_cvt_pk_f32_fp8_sdwa v[80:81], v96 src0_sel:WORD_1
	v_cvt_pk_f32_fp8_e32 v[82:83], v97
	v_cvt_pk_f32_fp8_sdwa v[84:85], v97 src0_sel:WORD_1
	v_cvt_pk_f32_fp8_e32 v[86:87], v98
	v_cvt_pk_f32_fp8_sdwa v[88:89], v98 src0_sel:WORD_1
	v_cvt_pk_f32_fp8_e32 v[90:91], v99
	v_cvt_pk_f32_fp8_sdwa v[92:93], v99 src0_sel:WORD_1
	v_pk_fma_f32 v[64:65], v[78:79], s[6:7], v[64:65] op_sel_hi:[1,0,1]
	v_pk_fma_f32 v[62:63], v[80:81], s[6:7], v[62:63] op_sel_hi:[1,0,1]
	v_pk_fma_f32 v[60:61], v[82:83], s[6:7], v[60:61] op_sel_hi:[1,0,1]
	v_pk_fma_f32 v[58:59], v[84:85], s[6:7], v[58:59] op_sel_hi:[1,0,1]
	v_pk_fma_f32 v[56:57], v[86:87], s[6:7], v[56:57] op_sel_hi:[1,0,1]
	v_pk_fma_f32 v[54:55], v[88:89], s[6:7], v[54:55] op_sel_hi:[1,0,1]
	v_pk_fma_f32 v[50:51], v[90:91], s[6:7], v[50:51] op_sel_hi:[1,0,1]
	v_pk_fma_f32 v[52:53], v[92:93], s[6:7], v[52:53] op_sel_hi:[1,0,1]
	s_branch .LBB0_1393
